# a33: attention E loop - first two QK MFMAs (and their row-sum adds) hoisted above the K/V prefetch address+load block after the tile barrier; address temps renamed to v222/223/226/227
# baseline (speedup 1.0000x reference)
.LBB0_633:
	s_setprio 1
	s_waitcnt vmcnt(5) lgkmcnt(11)
	v_mfma_f32_32x32x16_bf16 v[32:47], v[32:35], v[84:87], 0
	v_add_f32_e32 v220, v163, v159
	v_add_f32_e32 v220, v204, v220
	v_add_f32_e32 v220, v173, v220
	s_waitcnt lgkmcnt(9)
	v_mfma_f32_32x32x16_bf16 v[48:63], v[128:131], v[84:87], 0
	v_add_f32_e32 v220, v205, v220
	v_add_f32_e32 v220, v190, v220
	v_add_f32_e32 v220, v206, v220
	s_add_i32 s22, s8, s41
	s_and_b32 s22, s22, 0x7f
	s_mulk_i32 s22, 0x3000
	v_lshl_add_u64 v[222:223], v[154:155], 0, s[22:23]
	global_load_dwordx4 v[140:143], v[222:223], off
	v_add_co_u32_e32 v222, vcc, s54, v222
	s_and_b32 s22, s9, 0xfe000
	s_nop 0
	v_addc_co_u32_e32 v223, vcc, 0, v223, vcc
	v_lshl_add_u64 v[226:227], v[152:153], 0, s[22:23]
	global_load_dwordx4 v[144:147], v[222:223], off
	global_load_dwordx4 v[136:139], v[226:227], off
	global_load_dwordx4 v[148:151], v[222:223], off offset:-4096
	global_load_dwordx4 v[132:135], v[226:227], off offset:64
	s_mov_b32 s22, s39
	s_mov_b32 s39, s59
	s_and_b32 s44, s41, 1
	s_add_i32 s41, s41, 1
	s_waitcnt vmcnt(9)
	v_mfma_f32_32x32x16_bf16 v[32:47], v[116:119], v[80:83], v[32:47]
	v_add_f32_e32 v220, v191, v220
	v_add_f32_e32 v220, v207, v220
	v_add_f32_e32 v220, v192, v220
	s_waitcnt lgkmcnt(8)
	v_mfma_f32_32x32x16_bf16 v[48:63], v[124:127], v[80:83], v[48:63]
	v_add_f32_e32 v220, v208, v220
	v_add_f32_e32 v220, v193, v220
	v_add_f32_e32 v220, v209, v220
	s_waitcnt vmcnt(8) lgkmcnt(7)
	v_mfma_f32_32x32x16_bf16 v[32:47], v[112:115], v[76:79], v[32:47]
	v_add_f32_e32 v220, v194, v220
	v_add_f32_e32 v220, v210, v220
	v_add_f32_e32 v220, v195, v220
	s_waitcnt lgkmcnt(5)
	v_mfma_f32_32x32x16_bf16 v[48:63], v[108:111], v[76:79], v[48:63]
	v_add_f32_e32 v220, v211, v220
	v_add_f32_e32 v220, v196, v220
	v_add_f32_e32 v220, v212, v220
	s_waitcnt vmcnt(7)
	v_mfma_f32_32x32x16_bf16 v[32:47], v[100:103], v[72:75], v[32:47]
	v_add_f32_e32 v220, v197, v220
	v_add_f32_e32 v220, v213, v220
	v_add_f32_e32 v220, v198, v220
	s_waitcnt lgkmcnt(4)
	v_mfma_f32_32x32x16_bf16 v[48:63], v[104:107], v[72:75], v[48:63]
	v_add_f32_e32 v220, v214, v220
	v_add_f32_e32 v220, v199, v220
	v_add_f32_e32 v220, v215, v220
	s_waitcnt vmcnt(6) lgkmcnt(3)
	v_mfma_f32_32x32x16_bf16 v[32:47], v[92:95], v[68:71], v[32:47]
	v_add_f32_e32 v220, v200, v220
	v_add_f32_e32 v220, v216, v220
	s_waitcnt lgkmcnt(1)
	v_mfma_f32_32x32x16_bf16 v[48:63], v[120:123], v[68:71], v[48:63]
	v_add_f32_e32 v220, v201, v220
	v_add_f32_e32 v220, v217, v220
	s_waitcnt vmcnt(5)
	v_mfma_f32_32x32x16_bf16 v[32:47], v[88:91], v[64:67], v[32:47]
	v_add_f32_e32 v220, v202, v220
	v_add_f32_e32 v220, v218, v220
	s_waitcnt lgkmcnt(0)
	v_mfma_f32_32x32x16_bf16 v[48:63], v[96:99], v[64:67], v[48:63]
	v_add_f32_e32 v220, v203, v220
	v_add_f32_e32 v159, v219, v220
	s_setprio 0
	s_mul_i32 s43, s44, 0x2400
	v_add_u32_e32 v100, s43, v157
	ds_read_b128 v[88:91], v100 offset:39936
	ds_read_b128 v[96:99], v100 offset:39968
	ds_read_b128 v[92:95], v100 offset:44544
	ds_read_b128 v[164:167], v100 offset:44576
	ds_read_b128 v[174:177], v100 offset:40000
	ds_read_b128 v[178:181], v100 offset:40032
	ds_read_b128 v[182:185], v100 offset:44608
	ds_read_b128 v[186:189], v100 offset:44640
	v_exp_f32_e32 v163, v32
	v_exp_f32_e32 v173, v33
	v_exp_f32_e32 v190, v34
	v_exp_f32_e32 v191, v35
	v_exp_f32_e32 v192, v36
	v_exp_f32_e32 v193, v37
	v_exp_f32_e32 v194, v38
	v_exp_f32_e32 v195, v39
	v_cvt_pk_bf16_f32 v36, v163, v173
	v_cvt_pk_bf16_f32 v37, v190, v191
	v_cvt_pk_bf16_f32 v38, v192, v193
	v_cvt_pk_bf16_f32 v39, v194, v195
	v_exp_f32_e32 v196, v40
	v_exp_f32_e32 v197, v41
	s_waitcnt lgkmcnt(7)
	v_mfma_f32_32x32x16_bf16 v[16:31], v[88:91], v[36:39], v[16:31]
	v_exp_f32_e32 v198, v42
	v_exp_f32_e32 v199, v43
	v_exp_f32_e32 v200, v44
	v_exp_f32_e32 v201, v45
	v_exp_f32_e32 v202, v46
	v_exp_f32_e32 v203, v47
	v_exp_f32_e32 v204, v48
	s_waitcnt lgkmcnt(5)
	v_mfma_f32_32x32x16_bf16 v[0:15], v[92:95], v[36:39], v[0:15]
	v_exp_f32_e32 v205, v49
	s_mul_i32 s43, s22, 0x3400
	v_add_u32_e32 v40, s43, v158
	v_cvt_pk_bf16_f32 v36, v196, v197
	v_cvt_pk_bf16_f32 v37, v198, v199
	v_cvt_pk_bf16_f32 v38, v200, v201
	v_cvt_pk_bf16_f32 v39, v202, v203
	v_exp_f32_e32 v206, v50
	ds_read_b128 v[32:35], v40
	ds_read_b128 v[116:119], v40 offset:32
	ds_read_b128 v[128:131], v40 offset:6656
	ds_read_b128 v[124:127], v40 offset:6688
	ds_read_b128 v[108:111], v40 offset:6720
	ds_read_b128 v[112:115], v40 offset:64
	ds_read_b128 v[100:103], v40 offset:96
	ds_read_b128 v[104:107], v40 offset:6752
	ds_read_b128 v[92:95], v40 offset:128
	ds_read_b128 v[88:91], v40 offset:160
	v_mfma_f32_32x32x16_bf16 v[16:31], v[96:99], v[36:39], v[16:31]
	ds_read_b128 v[120:123], v40 offset:6784
	ds_read_b128 v[96:99], v40 offset:6816
	v_cvt_pk_bf16_f32 v40, v204, v205
	v_exp_f32_e32 v207, v51
	s_waitcnt lgkmcnt(14)
	v_mfma_f32_32x32x16_bf16 v[0:15], v[164:167], v[36:39], v[0:15]
	v_exp_f32_e32 v208, v52
	v_exp_f32_e32 v209, v53
	v_exp_f32_e32 v210, v54
	v_exp_f32_e32 v211, v55
	v_cvt_pk_bf16_f32 v41, v206, v207
	v_cvt_pk_bf16_f32 v42, v208, v209
	v_cvt_pk_bf16_f32 v43, v210, v211
	v_exp_f32_e32 v212, v56
	v_exp_f32_e32 v213, v57
	v_mfma_f32_32x32x16_bf16 v[16:31], v[174:177], v[40:43], v[16:31]
	v_exp_f32_e32 v214, v58
	v_exp_f32_e32 v215, v59
	v_exp_f32_e32 v216, v60
	v_exp_f32_e32 v217, v61
	v_exp_f32_e32 v218, v62
	v_exp_f32_e32 v219, v63
	s_waitcnt lgkmcnt(13)
	v_mfma_f32_32x32x16_bf16 v[0:15], v[182:185], v[40:43], v[0:15]
	v_cvt_pk_bf16_f32 v36, v212, v213
	v_cvt_pk_bf16_f32 v37, v214, v215
	v_cvt_pk_bf16_f32 v38, v216, v217
	v_cvt_pk_bf16_f32 v39, v218, v219
	s_nop 1
	v_mfma_f32_32x32x16_bf16 v[16:31], v[178:181], v[36:39], v[16:31]
	s_waitcnt lgkmcnt(12)
	v_mfma_f32_32x32x16_bf16 v[0:15], v[186:189], v[36:39], v[0:15]
	s_mul_i32 s43, s59, 0x3400
	s_xor_b32 s44, s44, 1
	s_addk_i32 s9, 0x2000
	s_mov_b32 s59, s42
	s_mov_b32 s42, s22
	s_add_i32 s22, s43, 0
	s_mulk_i32 s44, 0x2400
	v_add_u32_e32 v38, s22, v160
	s_cmpk_lg_i32 s41, 0x7e
	v_add_u32_e32 v36, s22, v162
	v_add_u32_e32 v37, s22, v161
	v_add_u32_e32 v39, s44, v156
	s_waitcnt vmcnt(4)
	ds_write_b128 v38, v[140:143]
	s_waitcnt vmcnt(1)
	ds_write_b128 v37, v[148:151]
	ds_write_b128 v36, v[144:147]
	ds_write_b16 v39, v136 offset:39936
	ds_write_b16_d16_hi v39, v136 offset:40080
	ds_write_b16 v39, v137 offset:40224
	ds_write_b16_d16_hi v39, v137 offset:40368
	ds_write_b16 v39, v138 offset:40512
	ds_write_b16_d16_hi v39, v138 offset:40656
	ds_write_b16 v39, v139 offset:40800
	ds_write_b16_d16_hi v39, v139 offset:40944
	s_waitcnt vmcnt(0)
	ds_write_b16 v39, v132 offset:44544
	ds_write_b16_d16_hi v39, v132 offset:44688
	ds_write_b16 v39, v133 offset:44832
	ds_write_b16_d16_hi v39, v133 offset:44976
	ds_write_b16 v39, v134 offset:45120
	ds_write_b16_d16_hi v39, v134 offset:45264
	ds_write_b16 v39, v135 offset:45408
	ds_write_b16_d16_hi v39, v135 offset:45552
	s_waitcnt lgkmcnt(0)
	s_barrier
	s_cbranch_scc1 .LBB0_633
	s_add_i32 s8, s40, 0xfe000
	s_and_b32 s22, s8, 0xfe000
	v_lshl_add_u64 v[36:37], v[152:153], 0, s[22:23]
	global_load_dwordx4 v[132:135], v[36:37], off
	global_load_dwordx4 v[136:139], v[36:37], off offset:64
	s_setprio 1
	v_mfma_f32_32x32x16_bf16 v[48:63], v[32:35], v[84:87], 0
	v_add_f32_e32 v220, v163, v159
	v_add_f32_e32 v220, v204, v220
	v_add_f32_e32 v220, v173, v220
	v_mfma_f32_32x32x16_bf16 v[32:47], v[128:131], v[84:87], 0
	v_add_f32_e32 v220, v205, v220
	v_add_f32_e32 v220, v190, v220
	v_add_f32_e32 v220, v206, v220
	v_mfma_f32_32x32x16_bf16 v[32:47], v[124:127], v[80:83], v[32:47]
	v_add_f32_e32 v220, v191, v220
	v_add_f32_e32 v220, v207, v220
	v_add_f32_e32 v220, v192, v220
	v_mfma_f32_32x32x16_bf16 v[48:63], v[116:119], v[80:83], v[48:63]
	v_add_f32_e32 v220, v208, v220
	v_add_f32_e32 v220, v193, v220
	v_add_f32_e32 v220, v209, v220
	v_mfma_f32_32x32x16_bf16 v[32:47], v[108:111], v[76:79], v[32:47]
	v_add_f32_e32 v220, v194, v220
	v_add_f32_e32 v220, v210, v220
	v_add_f32_e32 v220, v195, v220
	v_mfma_f32_32x32x16_bf16 v[48:63], v[112:115], v[76:79], v[48:63]
	v_add_f32_e32 v220, v211, v220
	v_add_f32_e32 v220, v196, v220
	v_add_f32_e32 v220, v212, v220
	v_mfma_f32_32x32x16_bf16 v[32:47], v[104:107], v[72:75], v[32:47]
	v_add_f32_e32 v220, v197, v220
	v_add_f32_e32 v220, v213, v220
	v_add_f32_e32 v220, v198, v220
	v_mfma_f32_32x32x16_bf16 v[48:63], v[100:103], v[72:75], v[48:63]
	v_add_f32_e32 v220, v214, v220
	v_add_f32_e32 v220, v199, v220
	v_add_f32_e32 v220, v215, v220
	v_mfma_f32_32x32x16_bf16 v[32:47], v[120:123], v[68:71], v[32:47]
	v_add_f32_e32 v220, v200, v220
	v_add_f32_e32 v220, v216, v220
	v_mfma_f32_32x32x16_bf16 v[48:63], v[92:95], v[68:71], v[48:63]
	v_add_f32_e32 v220, v201, v220
	v_add_f32_e32 v220, v217, v220
	v_mfma_f32_32x32x16_bf16 v[32:47], v[96:99], v[64:67], v[32:47]
	v_add_f32_e32 v220, v202, v220
	v_add_f32_e32 v220, v218, v220
	v_mfma_f32_32x32x16_bf16 v[48:63], v[88:91], v[64:67], v[48:63]
	v_add_f32_e32 v220, v203, v220
	v_add_f32_e32 v159, v219, v220
	s_setprio 0
	ds_read_b128 v[88:91], v157 offset:39936
	ds_read_b128 v[92:95], v157 offset:39968
	ds_read_b128 v[96:99], v157 offset:44544
	ds_read_b128 v[100:103], v157 offset:44576
	ds_read_b128 v[104:107], v157 offset:40000
	ds_read_b128 v[108:111], v157 offset:40032
	ds_read_b128 v[112:115], v157 offset:44608
	ds_read_b128 v[116:119], v157 offset:44640
	s_nop 2
	v_exp_f32_e32 v140, v48
	v_exp_f32_e32 v141, v49
	v_exp_f32_e32 v142, v50
	v_exp_f32_e32 v143, v51
	v_exp_f32_e32 v52, v52
	v_exp_f32_e32 v53, v53
	v_exp_f32_e32 v54, v54
	v_exp_f32_e32 v55, v55
	v_cvt_pk_bf16_f32 v48, v140, v141
	v_cvt_pk_bf16_f32 v49, v142, v143
	v_cvt_pk_bf16_f32 v50, v52, v53
	v_cvt_pk_bf16_f32 v51, v54, v55
	v_exp_f32_e32 v56, v56
	v_exp_f32_e32 v57, v57
	s_waitcnt lgkmcnt(7)
	v_mfma_f32_32x32x16_bf16 v[16:31], v[88:91], v[48:51], v[16:31]
	v_exp_f32_e32 v58, v58
	v_exp_f32_e32 v59, v59
	v_exp_f32_e32 v60, v60
	v_exp_f32_e32 v61, v61
	v_exp_f32_e32 v62, v62
	v_exp_f32_e32 v63, v63
	v_exp_f32_e32 v144, v32
	s_waitcnt lgkmcnt(5)
	v_mfma_f32_32x32x16_bf16 v[0:15], v[96:99], v[48:51], v[0:15]
	v_cvt_pk_bf16_f32 v48, v56, v57
	v_cvt_pk_bf16_f32 v49, v58, v59
	v_cvt_pk_bf16_f32 v50, v60, v61
	v_cvt_pk_bf16_f32 v51, v62, v63
	v_exp_f32_e32 v145, v33
	v_exp_f32_e32 v146, v34
	v_exp_f32_e32 v147, v35
	v_mfma_f32_32x32x16_bf16 v[16:31], v[92:95], v[48:51], v[16:31]
	v_exp_f32_e32 v148, v36
	v_cvt_pk_bf16_f32 v32, v144, v145
	v_cvt_pk_bf16_f32 v33, v146, v147
	v_exp_f32_e32 v149, v41
	v_exp_f32_e32 v150, v42
	v_exp_f32_e32 v151, v43
	v_exp_f32_e32 v44, v44
	s_waitcnt lgkmcnt(4)
	v_mfma_f32_32x32x16_bf16 v[0:15], v[100:103], v[48:51], v[0:15]
	v_exp_f32_e32 v48, v37
	v_exp_f32_e32 v49, v38
	v_exp_f32_e32 v50, v39
	v_exp_f32_e32 v51, v40
	v_cvt_pk_bf16_f32 v34, v148, v48
	v_exp_f32_e32 v45, v45
	v_cvt_pk_bf16_f32 v35, v49, v50
	v_exp_f32_e32 v46, v46
	v_exp_f32_e32 v47, v47
	s_waitcnt lgkmcnt(3)
	v_mfma_f32_32x32x16_bf16 v[16:31], v[104:107], v[32:35], v[16:31]
	v_add_u32_e32 v128, s43, v158
	s_waitcnt lgkmcnt(1)
	v_mfma_f32_32x32x16_bf16 v[0:15], v[112:115], v[32:35], v[0:15]
	v_cvt_pk_bf16_f32 v32, v51, v149
	v_cvt_pk_bf16_f32 v33, v150, v151
	v_cvt_pk_bf16_f32 v34, v44, v45
	v_cvt_pk_bf16_f32 v35, v46, v47
	s_nop 1
	v_mfma_f32_32x32x16_bf16 v[16:31], v[108:111], v[32:35], v[16:31]
	ds_read_b128 v[36:39], v128
	ds_read_b128 v[88:91], v128 offset:32
	ds_read_b128 v[40:43], v128 offset:6656
	ds_read_b128 v[92:95], v128 offset:6688
	ds_read_b128 v[96:99], v128 offset:64
	ds_read_b128 v[100:103], v128 offset:96
	ds_read_b128 v[104:107], v128 offset:6720
	ds_read_b128 v[108:111], v128 offset:6752
	ds_read_b128 v[112:115], v128 offset:128
	ds_read_b128 v[120:123], v128 offset:160
	ds_read_b128 v[124:127], v128 offset:6784
	ds_read_b128 v[128:131], v128 offset:6816
	s_waitcnt lgkmcnt(12)
	v_mfma_f32_32x32x16_bf16 v[0:15], v[116:119], v[32:35], v[0:15]
	v_add_f32_e32 v32, v159, v140
	v_add_f32_e32 v32, v144, v32
	v_add_f32_e32 v32, v141, v32
	v_add_f32_e32 v32, v145, v32
	v_add_f32_e32 v32, v142, v32
	v_add_f32_e32 v32, v146, v32
	v_add_f32_e32 v32, v143, v32
	v_add_f32_e32 v32, v147, v32
	v_add_f32_e32 v32, v52, v32
	v_add_f32_e32 v32, v148, v32
	v_add_f32_e32 v32, v53, v32
	v_add_f32_e32 v32, v48, v32
	v_add_f32_e32 v32, v54, v32
	v_add_f32_e32 v32, v49, v32
	v_add_f32_e32 v32, v55, v32
	v_add_f32_e32 v32, v50, v32
	v_add_f32_e32 v32, v56, v32
	v_add_f32_e32 v32, v51, v32
	v_add_f32_e32 v32, v57, v32
	v_add_f32_e32 v32, v149, v32
	v_add_f32_e32 v32, v58, v32
	v_add_f32_e32 v32, v150, v32
	v_add_f32_e32 v32, v59, v32
	v_add_f32_e32 v32, v151, v32
	v_add_f32_e32 v32, v60, v32
	v_add_f32_e32 v32, v44, v32
	v_add_f32_e32 v32, v61, v32
	v_add_f32_e32 v32, v45, v32
	v_add_f32_e32 v32, v62, v32
	v_add_f32_e32 v32, v46, v32
	v_add_f32_e32 v32, v63, v32
	v_add_f32_e32 v116, v47, v32
	s_waitcnt vmcnt(1)
	ds_write_b16 v156, v132 offset:49152
	ds_write_b16_d16_hi v156, v132 offset:49296
	ds_write_b16 v156, v133 offset:49440
	ds_write_b16_d16_hi v156, v133 offset:49584
	ds_write_b16 v156, v134 offset:49728
	ds_write_b16_d16_hi v156, v134 offset:49872
	ds_write_b16 v156, v135 offset:50016
	ds_write_b16_d16_hi v156, v135 offset:50160
	s_waitcnt vmcnt(0)
	ds_write_b16 v156, v136 offset:53760
	ds_write_b16_d16_hi v156, v136 offset:53904
	ds_write_b16 v156, v137 offset:54048
	ds_write_b16_d16_hi v156, v137 offset:54192
	ds_write_b16 v156, v138 offset:54336
	ds_write_b16_d16_hi v156, v138 offset:54480
	ds_write_b16 v156, v139 offset:54624
	ds_write_b16_d16_hi v156, v139 offset:54768
	s_waitcnt lgkmcnt(0)
	s_barrier
	s_setprio 1
	v_mfma_f32_32x32x16_bf16 v[48:63], v[36:39], v[84:87], 0
	v_mfma_f32_32x32x16_bf16 v[32:47], v[40:43], v[84:87], 0
	v_mfma_f32_32x32x16_bf16 v[32:47], v[92:95], v[80:83], v[32:47]
	v_mfma_f32_32x32x16_bf16 v[48:63], v[88:91], v[80:83], v[48:63]
	v_mfma_f32_32x32x16_bf16 v[32:47], v[104:107], v[76:79], v[32:47]
	v_mfma_f32_32x32x16_bf16 v[48:63], v[96:99], v[76:79], v[48:63]
	v_mfma_f32_32x32x16_bf16 v[32:47], v[108:111], v[72:75], v[32:47]
	v_mfma_f32_32x32x16_bf16 v[48:63], v[100:103], v[72:75], v[48:63]
	v_mfma_f32_32x32x16_bf16 v[32:47], v[124:127], v[68:71], v[32:47]
	v_mfma_f32_32x32x16_bf16 v[48:63], v[112:115], v[68:71], v[48:63]
	v_mfma_f32_32x32x16_bf16 v[32:47], v[128:131], v[64:67], v[32:47]
	v_mfma_f32_32x32x16_bf16 v[48:63], v[120:123], v[64:67], v[48:63]
	s_setprio 0
	ds_read_b128 v[64:67], v157 offset:49152
	ds_read_b128 v[68:71], v157 offset:49184
	ds_read_b128 v[72:75], v157 offset:53760
	ds_read_b128 v[76:79], v157 offset:53792
	ds_read_b128 v[80:83], v157 offset:49216
	ds_read_b128 v[84:87], v157 offset:49248
	ds_read_b128 v[88:91], v157 offset:53824
	ds_read_b128 v[92:95], v157 offset:53856
	s_nop 2
	v_exp_f32_e32 v96, v48
	v_exp_f32_e32 v97, v49
	v_exp_f32_e32 v98, v50
	v_exp_f32_e32 v99, v51
	v_exp_f32_e32 v52, v52
	v_exp_f32_e32 v53, v53
	v_exp_f32_e32 v54, v54
	v_exp_f32_e32 v55, v55
	v_cvt_pk_bf16_f32 v48, v96, v97
	v_cvt_pk_bf16_f32 v49, v98, v99
	v_cvt_pk_bf16_f32 v50, v52, v53
	v_cvt_pk_bf16_f32 v51, v54, v55
	v_exp_f32_e32 v56, v56
	v_exp_f32_e32 v57, v57
	s_waitcnt lgkmcnt(7)
	v_mfma_f32_32x32x16_bf16 v[16:31], v[64:67], v[48:51], v[16:31]
	v_exp_f32_e32 v58, v58
	v_exp_f32_e32 v59, v59
	v_exp_f32_e32 v60, v60
	v_exp_f32_e32 v61, v61
	v_exp_f32_e32 v62, v62
	v_exp_f32_e32 v63, v63
	v_exp_f32_e32 v64, v32
	s_waitcnt lgkmcnt(5)
	v_mfma_f32_32x32x16_bf16 v[0:15], v[72:75], v[48:51], v[0:15]
	v_cvt_pk_bf16_f32 v48, v56, v57
	v_cvt_pk_bf16_f32 v49, v58, v59
	v_cvt_pk_bf16_f32 v50, v60, v61
	v_cvt_pk_bf16_f32 v51, v62, v63
	v_exp_f32_e32 v65, v33
	v_exp_f32_e32 v66, v34
	v_exp_f32_e32 v67, v35
	v_mfma_f32_32x32x16_bf16 v[16:31], v[68:71], v[48:51], v[16:31]
	v_exp_f32_e32 v36, v36
	v_exp_f32_e32 v37, v37
	v_exp_f32_e32 v38, v38
	v_exp_f32_e32 v39, v39
	v_cvt_pk_bf16_f32 v32, v64, v65
	v_cvt_pk_bf16_f32 v33, v66, v67
	v_cvt_pk_bf16_f32 v34, v36, v37
	s_waitcnt lgkmcnt(4)
	v_mfma_f32_32x32x16_bf16 v[0:15], v[76:79], v[48:51], v[0:15]
	v_cvt_pk_bf16_f32 v35, v38, v39
	v_add_f32_e32 v48, v116, v96
	v_add_f32_e32 v48, v64, v48
	v_exp_f32_e32 v40, v40
	v_exp_f32_e32 v41, v41
	v_exp_f32_e32 v42, v42
	v_exp_f32_e32 v43, v43
	s_waitcnt lgkmcnt(3)
	v_mfma_f32_32x32x16_bf16 v[16:31], v[80:83], v[32:35], v[16:31]
	v_exp_f32_e32 v44, v44
	v_exp_f32_e32 v45, v45
	v_exp_f32_e32 v46, v46
	v_exp_f32_e32 v47, v47
	v_add_f32_e32 v48, v97, v48
	v_add_f32_e32 v48, v65, v48
	v_add_f32_e32 v48, v98, v48
	s_waitcnt lgkmcnt(1)
	v_mfma_f32_32x32x16_bf16 v[0:15], v[88:91], v[32:35], v[0:15]
	v_add_f32_e32 v48, v66, v48
	v_cvt_pk_bf16_f32 v32, v40, v41
	v_cvt_pk_bf16_f32 v33, v42, v43
	v_cvt_pk_bf16_f32 v34, v44, v45
	v_cvt_pk_bf16_f32 v35, v46, v47
	v_add_f32_e32 v48, v99, v48
	s_waitcnt lgkmcnt(0)
	v_mfma_f32_32x32x16_bf16 v[16:31], v[84:87], v[32:35], v[16:31]
	s_barrier
	v_mfma_f32_32x32x16_bf16 v[0:15], v[92:95], v[32:35], v[0:15]
	v_add_f32_e32 v32, v67, v48
	v_add_f32_e32 v32, v52, v32
	v_add_f32_e32 v32, v36, v32
	v_add_f32_e32 v32, v53, v32
	v_add_f32_e32 v32, v37, v32
	v_add_f32_e32 v32, v54, v32
	v_add_f32_e32 v32, v38, v32
	v_add_f32_e32 v32, v55, v32
	v_add_f32_e32 v32, v39, v32
	v_add_f32_e32 v32, v56, v32
	v_add_f32_e32 v32, v40, v32
	v_add_f32_e32 v32, v57, v32
	v_add_f32_e32 v32, v41, v32
	v_add_f32_e32 v32, v58, v32
	v_add_f32_e32 v32, v42, v32
	v_add_f32_e32 v32, v59, v32
	v_add_f32_e32 v32, v43, v32
	v_add_f32_e32 v32, v60, v32
	v_add_f32_e32 v32, v44, v32
	v_add_f32_e32 v32, v61, v32
	v_add_f32_e32 v32, v45, v32
	v_add_f32_e32 v32, v62, v32
	v_add_f32_e32 v32, v46, v32
	v_add_f32_e32 v32, v63, v32
	v_add_f32_e32 v32, v47, v32
	v_mov_b32_e32 v33, v32
	s_nop 1
	v_permlane32_swap_b32_e32 v32, v33
	s_branch .LBB0_592
